# P4 SwiGLU epilogue: 7 of the 8 per-row rms sums fetched one unit ahead (end of previous epilogue / before first unit) so the epilogue does not wait on them
# speedup vs baseline: 1.0043x; 1.0017x over previous
; #define PG8_WAIT_V(n) asm volatile("s_waitcnt vmcnt(" #n ")" ::: "memory")
; #define PG8_BAR __builtin_amdgcn_s_barrier()
;     const int tid = threadIdx.x, wid = __builtin_amdgcn_readfirstlane(tid >> 6), lane = tid & 63, wr = wid >> 2, wc = wid & 3, fr = lane & 15, fq = lane >> 4;
;     const int K = g.K, nt = K / BK;
;     unsigned voffA[2], voffB[2];
; #pragma unroll
;     for (int i = 0; i < 2; ++i) { int R, C; stage_rc(tid * 16 + i * 8192, R, C); const int Rb = Epi::PERM ? ((R & ~31) + perm32(R & 31)) : R;
;         voffA[i] = (unsigned)(R * K + C) * 2u; voffB[i] = (unsigned)(Rb * K + C) * 2u; }
;     const size_t kstep = (size_t)(BK * 2);
;     const size_t hstep = (size_t)HALF * K * 2;
;     const size_t tstep = 2 * hstep;
;     const unsigned ldsw = (unsigned)wid * 1024u;
;     const unsigned ldsbw = (unsigned)__builtin_amdgcn_readfirstlane((unsigned)(uintptr_t)lds + ldsw);
;     const int aoff = lds_byte(wr * 64 + fr, fq * 8), boff = lds_byte(wc * 32 + fr, fq * 8);
;     ...
;     Unit cur, nxt; int ui = 0;
;     if (!S.next(0, cur)) return;
;     f32x4 acc[2][2][4][2];
; #pragma unroll
;     for (int a = 0; a < 2; ++a)
; #pragma unroll
;         for (int b = 0; b < 2; ++b)
; #pragma unroll
;             for (int m = 0; m < 4; ++m)
; #pragma unroll
;                 for (int n = 0; n < 2; ++n) acc[a][b][m][n] = (f32x4){0.f, 0.f, 0.f, 0.f};
;     f16x8 At[4][2], B0[2][2], B1[2][2];
;     if constexpr (ABL & 4) { _Pragma("unroll") for (int m = 0; m < 4; ++m) _Pragma("unroll") for (int k = 0; k < 2; ++k) { At[m][k] = (f16x8)(_Float16)(float)(lane * 0.001f); asm volatile("" : "+v"(At[m][k])); }
;         _Pragma("unroll") for (int n = 0; n < 2; ++n) _Pragma("unroll") for (int k = 0; k < 2; ++k) { B0[n][k] = At[n][k]; B1[n][k] = At[n + 2][k]; } }
;     const char* cA = (const char*)g.A + (size_t)cur.pm * tstep; const char* cB = (const char*)g.Bt + (size_t)cur.pn * tstep;
;     S.a_ready(cur);
;     if constexpr (SP2) {
;         PG8_STAGE(PG8_SB(0, 0), cB, voffB); PG8_STAGE(PG8_SB(0, 1), cB + hstep, voffB); PG8_STAGE(PG8_SA(0, 0), cA, voffA); PG8_STAGE(PG8_SA(0, 1), cA + hstep, voffA);
;         if (wr == 1) PG8_BAR;
;         PG8_WAIT_V(2); PG8_BAR;
;         PG8_STAGE(PG8_SB(1, 0), cB + kstep, voffB); PG8_STAGE(PG8_SA(1, 0), cA + kstep, voffA); PG8_STAGE(PG8_SB(1, 1), cB + hstep + kstep, voffB);
;         PG8_WAIT_V(6); PG8_BAR;
;     } else {
.LBB0_832:
	s_cmp_lt_i32 s76, 5
	s_cselect_b64 s[4:5], -1, 0
	s_add_u32 s12, s22, 0x3d00000
	s_addc_u32 s13, s23, 0
	s_add_u32 s18, s22, 0x5d00000
	s_addc_u32 s19, s23, 0
	s_and_b64 s[16:17], s[4:5], s[2:3]
	s_andn2_b64 vcc, exec, s[16:17]
	s_cbranch_vccnz .LBB0_894
	v_lshlrev_b32_e32 v1, 4, v0
	s_waitcnt vmcnt(1)
	v_and_b32_e32 v2, 32, v0
	v_bitop3_b32 v1, v1, v2, 48 bitop3:0x6c
	v_and_or_b32 v201, v0, 64, v1
	v_lshrrev_b32_e32 v1, 1, v0
	v_lshrrev_b32_e32 v2, 5, v0
	v_and_b32_e32 v1, 24, v1
	v_and_b32_e32 v2, 4, v2
	v_bfe_u32 v4, v0, 2, 2
	s_waitcnt lgkmcnt(0)
	v_bfe_u32 v3, v0, 2, 4
	v_or3_b32 v1, v2, v4, v1
	v_lshrrev_b32_e32 v2, 3, v0
	v_and_or_b32 v203, v2, 48, v3
	v_and_or_b32 v202, v2, 32, v1
	v_bfe_u32 v2, v0, 3, 25
	v_or_b32_e32 v2, 64, v2
	s_movk_i32 s2, 0x70
	v_readfirstlane_b32 s3, v0
	v_and_or_b32 v204, v2, s2, v3
	s_movk_i32 s2, 0x60
	v_lshlrev_b32_e32 v198, 6, v0
	v_lshlrev_b32_e32 v3, 2, v0
	v_and_or_b32 v205, v2, s2, v1
	s_lshr_b32 s4, s3, 6
	v_and_b32_e32 v1, 48, v0
	v_and_b32_e32 v2, 0x3c0, v198
	v_and_b32_e32 v200, 32, v3
	s_cmpk_gt_i32 s10, 0x57f
	v_bitop3_b32 v199, v2, v200, v1 bitop3:0x36
	s_cbranch_scc1 .LBB0_859
	s_lshl_b32 s2, s4, 10
	s_ashr_i32 s15, s10, 31
	s_add_i32 s14, s2, 0
	s_lshr_b32 s2, s15, 29
	s_add_i32 s2, s10, s2
	s_ashr_i32 s6, s2, 3
	s_and_b32 s2, s2, -8
	s_lshr_b32 s5, s3, 8
	s_sub_i32 s2, s10, s2
	s_cmp_lt_i32 s2, 0
	s_movk_i32 s28, 0xb1
	s_cselect_b32 s7, s28, 0xb0
	s_mul_i32 s2, s2, s7
	s_add_i32 s2, s2, s6
	s_mul_hi_i32 s6, s2, 0x2e8ba2e9
	s_lshr_b32 s7, s6, 31
	s_ashr_i32 s6, s6, 5
	s_add_i32 s6, s6, s7
	s_lshl_b32 s7, s6, 3
	s_mulk_i32 s6, 0xb0
	s_sub_i32 s6, s2, s6
	s_sext_i32_i16 s2, s6
	s_bfe_u32 s2, s2, 0x3001c
	s_add_i32 s8, s6, s2
	s_sext_i32_i16 s2, s8
	s_and_b32 s8, s8, 0xfff8
	s_sub_i32 s6, s6, s8
	s_sext_i32_i16 s6, s6
	s_add_i32 s46, s7, s6
	s_ashr_i32 s47, s46, 31
	s_lshl_b32 s20, s46, 8
	s_lshl_b32 s21, s5, 6
	s_add_i32 s20, s20, s21
	v_and_or_b32 v2, v0, 15, s20
	v_mov_b32_e32 v3, 0
	v_lshl_add_u64 v[2:3], v[2:3], 2, s[0:1]
	global_load_dword v248, v[2:3], off
	global_load_dword v249, v[2:3], off offset:64
	global_load_dword v250, v[2:3], off offset:512
	global_load_dword v251, v[2:3], off offset:576
	global_load_dword v252, v[2:3], off offset:640
	global_load_dword v253, v[2:3], off offset:128
	global_load_dword v255, v[2:3], off offset:192
	s_lshr_b32 s2, s2, 3
	s_lshl_b64 s[6:7], s[46:47], 19
	s_add_u32 s8, s74, s6
	s_addc_u32 s9, s75, s7
	s_bfe_i64 s[6:7], s[2:3], 0x100000
	s_lshl_b64 s[6:7], s[6:7], 19
	s_add_u32 s6, s58, s6
	v_lshl_or_b32 v207, v202, 11, v201
	s_addc_u32 s7, s59, s7
	s_add_u32 m0, s14, 0x10000
	s_nop 0
	global_load_lds_dwordx4 v207, s[6:7]
	v_lshl_or_b32 v209, v205, 11, v201
	s_add_u32 m0, s14, 0x12000
	s_nop 0
	global_load_lds_dwordx4 v209, s[6:7]
	s_add_u32 s20, s6, 0x40000
	s_addc_u32 s21, s7, 0
	s_add_u32 m0, s14, 0x14000
	s_nop 0
	global_load_lds_dwordx4 v207, s[20:21]
	v_lshl_or_b32 v206, v203, 11, v201
	s_add_u32 m0, s14, 0x16000
	s_nop 0
	global_load_lds_dwordx4 v209, s[20:21]
	v_lshl_or_b32 v208, v204, 11, v201
	s_add_u32 m0, s14, 0
	s_nop 0
	global_load_lds_dwordx4 v206, s[8:9]
	s_mov_b32 s29, 0
	s_add_u32 m0, s14, 0x2000
	s_nop 0
	global_load_lds_dwordx4 v208, s[8:9]
	s_add_u32 s20, s8, 0x40000
	s_addc_u32 s21, s9, 0
	s_add_u32 m0, s14, 0x4000
	s_nop 0
	global_load_lds_dwordx4 v206, s[20:21]
	s_nop 0
	s_add_u32 m0, s14, 0x6000
	s_nop 0
	global_load_lds_dwordx4 v208, s[20:21]
	s_cmp_eq_u32 s5, 1
	s_cselect_b64 s[20:21], -1, 0
	s_cmp_lg_u32 s5, 1
	s_cbranch_scc1 .LBB0_836
	s_barrier

; __device__ __forceinline__ unsigned pkh7(float lo, float hi) { return (pkh(lo, hi) + 0x00080008u) & 0xFFF0FFF0u; }
;     __device__ __forceinline__ void operator()(const f32x4 (&acc)[2][2][4][2], const Unit& u, int wr, int wc, int fr_, int fq_) const {
;         int t_ = threadIdx.x; asm volatile("" : "+v"(t_)); const int fr = t_ & 15, fq = (t_ >> 4) & 3;
;         const int row0 = u.pm * BM + wr * 64 + fr; const int col0 = u.pn * HALF + wc * 32 + 8 * fq;
;         float rsv[2][4];
; #pragma unroll
;         for (int ai = 0; ai < 2; ++ai)
; #pragma unroll
;             for (int m = 0; m < 4; ++m) rsv[ai][m] = rowss[row0 + ai * HALF + m * 16];
; #pragma unroll
;         for (int ai = 0; ai < 2; ++ai)
; #pragma unroll
;             for (int m = 0; m < 4; ++m) {
;                 const int row = row0 + ai * HALF + m * 16;
;                 const float rs = __builtin_amdgcn_rsqf(rsv[ai][m] * (1.0f / D) + EPS);
;                 const float nrsl = -rs * LOG2E, irs2 = rsv[ai][m] * (1.0f / D) + EPS;
;                 f32x4 hv[2];
; #pragma unroll
;                 for (int n = 0; n < 2; ++n) {
;                     const f32x4 g = acc[ai][0][m][n], up = acc[ai][1][m][n];
;                     const f32x4 a = g * nrsl; f32x4 ex;
; #pragma unroll
;                     for (int e = 0; e < 4; ++e) ex[e] = __builtin_amdgcn_exp2f(a[e]);
;                     const f32x4 dn = ex * irs2 + irs2; f32x4 rc;
; #pragma unroll
;                     for (int e = 0; e < 4; ++e) rc[e] = __builtin_amdgcn_rcpf(dn[e]);
;                     hv[n] = (g * up) * rc;
;                 }
;                 u32x4 w; w.x = pkh7(hv[0][0], hv[0][1]); w.y = pkh7(hv[0][2], hv[0][3]); w.z = pkh7(hv[1][0], hv[1][1]); w.w = pkh7(hv[1][2], hv[1][3]);
;                 *(u32x4*)(Hd + (size_t)row * DFF + col0) = w;
.LBB0_853:
.LBB0_855:
	s_lshl_b32 s4, s46, 8
	v_mov_b32_e32 v144, v0
	s_add_i32 s4, s4, s30
	v_pk_mul_f32 v[142:143], v[106:107], v[118:119]
	v_and_or_b32 v132, v144, 15, s4
	v_ashrrev_i32_e32 v133, 31, v132
	v_lshl_add_u64 v[134:135], v[132:133], 2, s[0:1]
	v_or_b32_e32 v130, 16, v132
	v_ashrrev_i32_e32 v131, 31, v130
	v_lshl_add_u64 v[136:137], v[130:131], 2, s[0:1]
	v_lshrrev_b32_e32 v118, 1, v144
	v_or_b32_e32 v144, 32, v132
	v_pk_mul_f32 v[140:141], v[108:109], v[120:121]
	v_or_b32_e32 v120, 48, v132
	v_ashrrev_i32_e32 v145, 31, v144
	v_ashrrev_i32_e32 v121, 31, v120
	v_lshl_add_u64 v[146:147], v[144:145], 2, s[0:1]
	v_lshl_add_u64 v[148:149], v[120:121], 2, s[0:1]
	s_nop 0
	s_nop 0
	global_load_dword v121, v[134:135], off offset:704
	v_pk_mul_f32 v[128:129], v[116:117], v[128:129]
	v_pk_mul_f32 v[126:127], v[114:115], v[126:127]
	v_pk_mul_f32 v[136:137], v[112:113], v[124:125]
	v_pk_mul_f32 v[138:139], v[110:111], v[122:123]
	s_lshl_b32 s4, s50, 7
	v_and_or_b32 v118, v118, 24, s4
	v_or_b32_e32 v118, s31, v118
	v_mov_b64_e32 v[122:123], s[18:19]
	v_ashrrev_i32_e32 v119, 31, v118
	v_add_u32_e32 v154, 0x80, v132
	v_add_u32_e32 v155, 0x90, v132
	v_add_u32_e32 v125, 0xa0, v132
	v_add_u32_e32 v124, 0xb0, v132
	v_mad_i64_i32 v[132:133], s[4:5], v132, s47, v[122:123]
	v_lshlrev_b64 v[118:119], 1, v[118:119]
	v_lshl_add_u64 v[132:133], v[132:133], 0, v[118:119]
	s_andn2_b64 vcc, exec, s[2:3]
	s_mov_b64 s[2:3], -1
	s_cmp_lg_u64 s[36:37], 0
	s_cbranch_scc0 .Lepi_nobar_p4
	s_barrier
.Lepi_nobar_p4:
	v_fmamk_f32 v134, v248, 0x3a800000, v215
	v_rsq_f32_e32 v135, v134
	v_fmamk_f32 v146, v249, 0x3a800000, v215
	v_rsq_f32_e32 v131, v146
	v_mul_f32_e32 v148, 0xbfb8aa3b, v135
	v_pk_mul_f32 v[116:117], v[116:117], v[148:149] op_sel_hi:[1,0]
	v_pk_mul_f32 v[114:115], v[114:115], v[148:149] op_sel_hi:[1,0]
	v_pk_mul_f32 v[112:113], v[112:113], v[148:149] op_sel_hi:[1,0]
	v_pk_mul_f32 v[110:111], v[110:111], v[148:149] op_sel_hi:[1,0]
	v_exp_f32_e32 v114, v114
	v_exp_f32_e32 v115, v115
	v_exp_f32_e32 v116, v116
	v_exp_f32_e32 v117, v117
	v_exp_f32_e32 v110, v110
	v_exp_f32_e32 v111, v111
	v_exp_f32_e32 v112, v112
	v_exp_f32_e32 v113, v113
	v_mul_f32_e32 v148, 0xbfb8aa3b, v131
	v_pk_mul_f32 v[108:109], v[108:109], v[148:149] op_sel_hi:[1,0]
	v_pk_mul_f32 v[106:107], v[106:107], v[148:149] op_sel_hi:[1,0]
	v_exp_f32_e32 v108, v108
	v_exp_f32_e32 v106, v106
	v_exp_f32_e32 v107, v107
	v_exp_f32_e32 v109, v109
	v_pk_fma_f32 v[116:117], v[134:135], v[116:117], v[134:135] op_sel_hi:[0,1,0]
	v_pk_fma_f32 v[114:115], v[134:135], v[114:115], v[134:135] op_sel_hi:[0,1,0]
	v_pk_fma_f32 v[112:113], v[134:135], v[112:113], v[134:135] op_sel_hi:[0,1,0]
	v_pk_fma_f32 v[110:111], v[134:135], v[110:111], v[134:135] op_sel_hi:[0,1,0]
	v_rcp_f32_e32 v114, v114
	v_rcp_f32_e32 v115, v115
	v_rcp_f32_e32 v116, v116
	v_rcp_f32_e32 v117, v117
	v_rcp_f32_e32 v110, v110
	v_rcp_f32_e32 v111, v111
	v_rcp_f32_e32 v112, v112
	v_rcp_f32_e32 v113, v113
	v_pk_fma_f32 v[108:109], v[146:147], v[108:109], v[146:147] op_sel_hi:[0,1,0]
	v_pk_fma_f32 v[106:107], v[146:147], v[106:107], v[146:147] op_sel_hi:[0,1,0]
	v_rcp_f32_e32 v134, v106
	v_rcp_f32_e32 v135, v107
	v_rcp_f32_e32 v152, v108
	v_rcp_f32_e32 v153, v109
	v_pk_mul_f32 v[106:107], v[128:129], v[116:117]
	v_pk_mul_f32 v[108:109], v[126:127], v[114:115]
	v_pk_mul_f32 v[112:113], v[136:137], v[112:113]
	v_pk_mul_f32 v[110:111], v[138:139], v[110:111]
	v_cvt_pk_f16_f32 v108, v108, v109
	v_cvt_pk_f16_f32 v106, v106, v107
	v_cvt_pk_f16_f32 v107, v110, v111
	v_cvt_pk_f16_f32 v109, v112, v113
	v_add_u32_e32 v108, 0x80008, v108
	v_add_u32_e32 v110, 0x80008, v106
	v_add_u32_e32 v111, 0x80008, v107
	v_add_u32_e32 v109, 0x80008, v109
	v_pk_mul_f32 v[150:151], v[100:101], v[148:149] op_sel_hi:[1,0]
	v_pk_mul_f32 v[148:149], v[98:99], v[148:149] op_sel_hi:[1,0]
	v_and_b32_e32 v106, 0xfff0fff0, v108
	v_and_b32_e32 v107, 0xfff0fff0, v110
	v_and_b32_e32 v108, 0xfff0fff0, v111
	v_and_b32_e32 v109, 0xfff0fff0, v109
	v_exp_f32_e32 v148, v148
	global_store_dwordx4 v[132:133], v[106:109], off
	v_exp_f32_e32 v149, v149
	v_pk_mul_f32 v[100:101], v[100:101], v[104:105]
	v_exp_f32_e32 v106, v150
	v_exp_f32_e32 v107, v151
	v_pk_fma_f32 v[112:113], v[146:147], v[148:149], v[146:147] op_sel_hi:[0,1,0]
	v_rcp_f32_e32 v112, v112
	v_rcp_f32_e32 v113, v113
	v_pk_fma_f32 v[106:107], v[146:147], v[106:107], v[146:147] op_sel_hi:[0,1,0]
	v_rcp_f32_e32 v106, v106
	v_rcp_f32_e32 v107, v107
	v_pk_mul_f32 v[98:99], v[98:99], v[102:103]
	v_pk_mul_f32 v[108:109], v[140:141], v[152:153]
	v_pk_mul_f32 v[110:111], v[142:143], v[134:135]
	v_pk_mul_f32 v[102:103], v[100:101], v[106:107]
	v_pk_mul_f32 v[100:101], v[98:99], v[112:113]
	v_cvt_pk_f16_f32 v98, v110, v111
	v_cvt_pk_f16_f32 v100, v100, v101
	v_cvt_pk_f16_f32 v101, v102, v103
	v_fmamk_f32 v102, v253, 0x3a800000, v215
	v_rsq_f32_e32 v103, v102
	v_cvt_pk_f16_f32 v99, v108, v109
	v_add_u32_e32 v98, 0x80008, v98
	v_add_u32_e32 v99, 0x80008, v99
	v_mul_f32_e32 v106, 0xbfb8aa3b, v103
	v_pk_mul_f32 v[108:109], v[92:93], v[106:107] op_sel_hi:[1,0]
	v_pk_mul_f32 v[110:111], v[90:91], v[106:107] op_sel_hi:[1,0]
	v_pk_mul_f32 v[92:93], v[92:93], v[96:97]
	v_pk_mul_f32 v[90:91], v[90:91], v[94:95]
	v_pk_mul_f32 v[94:95], v[84:85], v[106:107] op_sel_hi:[1,0]
	v_pk_mul_f32 v[96:97], v[82:83], v[106:107] op_sel_hi:[1,0]
	v_exp_f32_e32 v94, v94
	v_exp_f32_e32 v96, v96
	v_exp_f32_e32 v95, v95
	v_exp_f32_e32 v97, v97
	v_exp_f32_e32 v110, v110
	v_exp_f32_e32 v111, v111
	v_pk_fma_f32 v[94:95], v[102:103], v[94:95], v[102:103] op_sel_hi:[0,1,0]
	v_pk_fma_f32 v[96:97], v[102:103], v[96:97], v[102:103] op_sel_hi:[0,1,0]
	v_rcp_f32_e32 v96, v96
; __device__ __forceinline__ unsigned pkh7(float lo, float hi) { return (pkh(lo, hi) + 0x00080008u) & 0xFFF0FFF0u; }
;     __device__ __forceinline__ void operator()(const f32x4 (&acc)[2][2][4][2], const Unit& u, int wr, int wc, int fr_, int fq_) const {
;     ...
; #pragma unroll
;         for (int ai = 0; ai < 2; ++ai)
; #pragma unroll
;             for (int m = 0; m < 4; ++m) {
;                 const int row = row0 + ai * HALF + m * 16;
;                 const float rs = __builtin_amdgcn_rsqf(rsv[ai][m] * (1.0f / D) + EPS);
;                 const float nrsl = -rs * LOG2E, irs2 = rsv[ai][m] * (1.0f / D) + EPS;
;                 f32x4 hv[2];
; #pragma unroll
;                 for (int n = 0; n < 2; ++n) {
;                     const f32x4 g = acc[ai][0][m][n], up = acc[ai][1][m][n];
;                     const f32x4 a = g * nrsl; f32x4 ex;
; #pragma unroll
;                     for (int e = 0; e < 4; ++e) ex[e] = __builtin_amdgcn_exp2f(a[e]);
;                     const f32x4 dn = ex * irs2 + irs2; f32x4 rc;
; #pragma unroll
;                     for (int e = 0; e < 4; ++e) rc[e] = __builtin_amdgcn_rcpf(dn[e]);
;                     hv[n] = (g * up) * rc;
;                 }
;                 u32x4 w; w.x = pkh7(hv[0][0], hv[0][1]); w.y = pkh7(hv[0][2], hv[0][3]); w.z = pkh7(hv[1][0], hv[1][1]); w.w = pkh7(hv[1][2], hv[1][3]);
;                 *(u32x4*)(Hd + (size_t)row * DFF + col0) = w;
;             }
	v_rcp_f32_e32 v94, v94
	v_rcp_f32_e32 v95, v95
	v_rcp_f32_e32 v97, v97
	v_exp_f32_e32 v108, v108
	v_exp_f32_e32 v109, v109
	v_add_u32_e32 v100, 0x80008, v100
	v_add_u32_e32 v101, 0x80008, v101
	v_mad_i64_i32 v[104:105], s[4:5], v130, s47, v[122:123]
	v_and_b32_e32 v98, 0xfff0fff0, v98
	v_and_b32_e32 v99, 0xfff0fff0, v99
	v_and_b32_e32 v100, 0xfff0fff0, v100
	v_and_b32_e32 v101, 0xfff0fff0, v101
	v_lshl_add_u64 v[104:105], v[104:105], 0, v[118:119]
	v_pk_mul_f32 v[84:85], v[84:85], v[88:89]
	v_pk_mul_f32 v[82:83], v[82:83], v[86:87]
	global_store_dwordx4 v[104:105], v[98:101], off
	v_pk_mul_f32 v[86:87], v[84:85], v[94:95]
	v_pk_mul_f32 v[84:85], v[82:83], v[96:97]
	v_pk_fma_f32 v[100:101], v[102:103], v[110:111], v[102:103] op_sel_hi:[0,1,0]
	v_pk_fma_f32 v[98:99], v[102:103], v[108:109], v[102:103] op_sel_hi:[0,1,0]
	v_rcp_f32_e32 v100, v100
	v_rcp_f32_e32 v101, v101
	v_cvt_pk_f16_f32 v84, v84, v85
	v_cvt_pk_f16_f32 v85, v86, v87
	v_fmamk_f32 v86, v255, 0x3a800000, v215
	v_rcp_f32_e32 v98, v98
	v_rcp_f32_e32 v99, v99
	v_rsq_f32_e32 v87, v86
	v_pk_mul_f32 v[90:91], v[90:91], v[100:101]
	v_add_u32_e32 v84, 0x80008, v84
	v_pk_mul_f32 v[92:93], v[92:93], v[98:99]
	v_cvt_pk_f16_f32 v82, v90, v91
	v_mul_f32_e32 v90, 0xbfb8aa3b, v87
	v_cvt_pk_f16_f32 v83, v92, v93
	v_pk_mul_f32 v[92:93], v[76:77], v[90:91] op_sel_hi:[1,0]
	v_pk_mul_f32 v[94:95], v[74:75], v[90:91] op_sel_hi:[1,0]
	v_pk_mul_f32 v[76:77], v[76:77], v[80:81]
	v_pk_mul_f32 v[74:75], v[74:75], v[78:79]
	v_pk_mul_f32 v[78:79], v[64:65], v[90:91] op_sel_hi:[1,0]
	v_pk_mul_f32 v[80:81], v[62:63], v[90:91] op_sel_hi:[1,0]
	v_exp_f32_e32 v78, v78
	v_exp_f32_e32 v80, v80
	v_exp_f32_e32 v79, v79
	v_exp_f32_e32 v81, v81
	v_exp_f32_e32 v94, v94
	v_exp_f32_e32 v95, v95
	v_pk_fma_f32 v[78:79], v[86:87], v[78:79], v[86:87] op_sel_hi:[0,1,0]
	v_pk_fma_f32 v[80:81], v[86:87], v[80:81], v[86:87] op_sel_hi:[0,1,0]
	v_rcp_f32_e32 v80, v80
	v_rcp_f32_e32 v78, v78
	v_rcp_f32_e32 v79, v79
	v_rcp_f32_e32 v81, v81
	v_exp_f32_e32 v92, v92
	v_exp_f32_e32 v93, v93
	v_add_u32_e32 v82, 0x80008, v82
	v_add_u32_e32 v83, 0x80008, v83
	v_add_u32_e32 v85, 0x80008, v85
	v_mad_i64_i32 v[88:89], s[4:5], v144, s47, v[122:123]
	v_and_b32_e32 v82, 0xfff0fff0, v82
	v_and_b32_e32 v83, 0xfff0fff0, v83
	v_and_b32_e32 v84, 0xfff0fff0, v84
	v_and_b32_e32 v85, 0xfff0fff0, v85
	v_lshl_add_u64 v[88:89], v[88:89], 0, v[118:119]
	v_pk_mul_f32 v[64:65], v[64:65], v[72:73]
	v_pk_mul_f32 v[62:63], v[62:63], v[70:71]
	global_store_dwordx4 v[88:89], v[82:85], off
	v_pk_mul_f32 v[70:71], v[64:65], v[78:79]
	v_pk_mul_f32 v[64:65], v[62:63], v[80:81]
	v_pk_fma_f32 v[84:85], v[86:87], v[94:95], v[86:87] op_sel_hi:[0,1,0]
	v_pk_fma_f32 v[82:83], v[86:87], v[92:93], v[86:87] op_sel_hi:[0,1,0]
	v_rcp_f32_e32 v84, v84
	v_rcp_f32_e32 v85, v85
	v_cvt_pk_f16_f32 v64, v64, v65
	v_cvt_pk_f16_f32 v65, v70, v71
	v_fmamk_f32 v70, v250, 0x3a800000, v215
	v_rcp_f32_e32 v82, v82
	v_rcp_f32_e32 v83, v83
	v_rsq_f32_e32 v71, v70
	v_pk_mul_f32 v[74:75], v[74:75], v[84:85]
	v_add_u32_e32 v64, 0x80008, v64
	v_pk_mul_f32 v[76:77], v[76:77], v[82:83]
	v_cvt_pk_f16_f32 v62, v74, v75
	v_mul_f32_e32 v74, 0xbfb8aa3b, v71
	v_cvt_pk_f16_f32 v63, v76, v77
	v_pk_mul_f32 v[76:77], v[60:61], v[74:75] op_sel_hi:[1,0]
	v_pk_mul_f32 v[78:79], v[58:59], v[74:75] op_sel_hi:[1,0]
	v_exp_f32_e32 v76, v76
	v_exp_f32_e32 v78, v78
	v_exp_f32_e32 v77, v77
	v_exp_f32_e32 v79, v79
	v_add_u32_e32 v62, 0x80008, v62
	v_add_u32_e32 v63, 0x80008, v63
	v_add_u32_e32 v65, 0x80008, v65
	v_mad_i64_i32 v[72:73], s[4:5], v120, s47, v[122:123]
	v_and_b32_e32 v62, 0xfff0fff0, v62
	v_and_b32_e32 v63, 0xfff0fff0, v63
	v_and_b32_e32 v64, 0xfff0fff0, v64
	v_and_b32_e32 v65, 0xfff0fff0, v65
	v_lshl_add_u64 v[72:73], v[72:73], 0, v[118:119]
	global_store_dwordx4 v[72:73], v[62:65], off
	v_pk_mul_f32 v[60:61], v[60:61], v[68:69]
	v_pk_mul_f32 v[58:59], v[58:59], v[66:67]
	v_pk_fma_f32 v[62:63], v[70:71], v[76:77], v[70:71] op_sel_hi:[0,1,0]
	v_pk_fma_f32 v[64:65], v[70:71], v[78:79], v[70:71] op_sel_hi:[0,1,0]
	v_pk_mul_f32 v[66:67], v[52:53], v[74:75] op_sel_hi:[1,0]
	v_pk_mul_f32 v[68:69], v[50:51], v[74:75] op_sel_hi:[1,0]
	v_rcp_f32_e32 v64, v64
	v_rcp_f32_e32 v65, v65
	v_rcp_f32_e32 v62, v62
	v_rcp_f32_e32 v63, v63
	v_exp_f32_e32 v68, v68
	v_exp_f32_e32 v66, v66
	v_exp_f32_e32 v67, v67
	v_exp_f32_e32 v69, v69
	v_pk_mul_f32 v[60:61], v[60:61], v[62:63]
	v_pk_mul_f32 v[58:59], v[58:59], v[64:65]
	v_pk_fma_f32 v[62:63], v[70:71], v[66:67], v[70:71] op_sel_hi:[0,1,0]
	v_pk_fma_f32 v[64:65], v[70:71], v[68:69], v[70:71] op_sel_hi:[0,1,0]
	v_rcp_f32_e32 v64, v64
	v_rcp_f32_e32 v62, v62
	v_rcp_f32_e32 v63, v63
	v_rcp_f32_e32 v65, v65
	v_pk_mul_f32 v[52:53], v[52:53], v[56:57]
	v_pk_mul_f32 v[50:51], v[50:51], v[54:55]
	v_pk_mul_f32 v[54:55], v[52:53], v[62:63]
	v_pk_mul_f32 v[52:53], v[50:51], v[64:65]
	v_cvt_pk_f16_f32 v50, v58, v59
	v_cvt_pk_f16_f32 v52, v52, v53
	v_cvt_pk_f16_f32 v53, v54, v55
	v_fmamk_f32 v54, v251, 0x3a800000, v215
	v_rsq_f32_e32 v55, v54
	v_cvt_pk_f16_f32 v51, v60, v61
	v_add_u32_e32 v50, 0x80008, v50
	v_add_u32_e32 v51, 0x80008, v51
	v_mul_f32_e32 v58, 0xbfb8aa3b, v55
	v_pk_mul_f32 v[60:61], v[44:45], v[58:59] op_sel_hi:[1,0]
	v_pk_mul_f32 v[62:63], v[42:43], v[58:59] op_sel_hi:[1,0]
	v_pk_mul_f32 v[44:45], v[44:45], v[48:49]
	v_pk_mul_f32 v[42:43], v[42:43], v[46:47]
	v_pk_mul_f32 v[46:47], v[36:37], v[58:59] op_sel_hi:[1,0]
	v_pk_mul_f32 v[48:49], v[34:35], v[58:59] op_sel_hi:[1,0]
	v_exp_f32_e32 v46, v46
	v_exp_f32_e32 v48, v48
	v_exp_f32_e32 v47, v47
	v_exp_f32_e32 v49, v49
	v_exp_f32_e32 v62, v62
	v_exp_f32_e32 v63, v63
	v_pk_fma_f32 v[46:47], v[54:55], v[46:47], v[54:55] op_sel_hi:[0,1,0]
; __device__ __forceinline__ unsigned pkh7(float lo, float hi) { return (pkh(lo, hi) + 0x00080008u) & 0xFFF0FFF0u; }
;     __device__ __forceinline__ void operator()(const f32x4 (&acc)[2][2][4][2], const Unit& u, int wr, int wc, int fr_, int fq_) const {
;     ...
;         float rsv[2][4];
; #pragma unroll
;         for (int ai = 0; ai < 2; ++ai)
; #pragma unroll
;             for (int m = 0; m < 4; ++m) rsv[ai][m] = rowss[row0 + ai * HALF + m * 16];
;     ...
;         for (int ai = 0; ai < 2; ++ai)
; #pragma unroll
;             for (int m = 0; m < 4; ++m) {
;                 const int row = row0 + ai * HALF + m * 16;
;                 const float rs = __builtin_amdgcn_rsqf(rsv[ai][m] * (1.0f / D) + EPS);
;                 const float nrsl = -rs * LOG2E, irs2 = rsv[ai][m] * (1.0f / D) + EPS;
;                 f32x4 hv[2];
; #pragma unroll
;                 for (int n = 0; n < 2; ++n) {
;                     const f32x4 g = acc[ai][0][m][n], up = acc[ai][1][m][n];
;                     const f32x4 a = g * nrsl; f32x4 ex;
; #pragma unroll
;                     for (int e = 0; e < 4; ++e) ex[e] = __builtin_amdgcn_exp2f(a[e]);
;                     const f32x4 dn = ex * irs2 + irs2; f32x4 rc;
; #pragma unroll
;                     for (int e = 0; e < 4; ++e) rc[e] = __builtin_amdgcn_rcpf(dn[e]);
;                     hv[n] = (g * up) * rc;
;                 }
;                 u32x4 w; w.x = pkh7(hv[0][0], hv[0][1]); w.y = pkh7(hv[0][2], hv[0][3]); w.z = pkh7(hv[1][0], hv[1][1]); w.w = pkh7(hv[1][2], hv[1][3]);
;                 *(u32x4*)(Hd + (size_t)row * DFF + col0) = w;
;             }
	v_pk_fma_f32 v[48:49], v[54:55], v[48:49], v[54:55] op_sel_hi:[0,1,0]
	v_rcp_f32_e32 v48, v48
	v_rcp_f32_e32 v46, v46
	v_rcp_f32_e32 v47, v47
	v_rcp_f32_e32 v49, v49
	v_exp_f32_e32 v60, v60
	v_exp_f32_e32 v61, v61
	v_add_u32_e32 v52, 0x80008, v52
	v_add_u32_e32 v53, 0x80008, v53
	v_mad_i64_i32 v[56:57], s[4:5], v154, s47, v[122:123]
	v_and_b32_e32 v50, 0xfff0fff0, v50
	v_and_b32_e32 v51, 0xfff0fff0, v51
	v_and_b32_e32 v52, 0xfff0fff0, v52
	v_and_b32_e32 v53, 0xfff0fff0, v53
	v_lshl_add_u64 v[56:57], v[56:57], 0, v[118:119]
	v_pk_mul_f32 v[36:37], v[36:37], v[40:41]
	v_pk_mul_f32 v[34:35], v[34:35], v[38:39]
	global_store_dwordx4 v[56:57], v[50:53], off
	v_pk_mul_f32 v[38:39], v[36:37], v[46:47]
	v_pk_mul_f32 v[36:37], v[34:35], v[48:49]
	v_pk_fma_f32 v[52:53], v[54:55], v[62:63], v[54:55] op_sel_hi:[0,1,0]
	v_pk_fma_f32 v[50:51], v[54:55], v[60:61], v[54:55] op_sel_hi:[0,1,0]
	v_rcp_f32_e32 v52, v52
	v_rcp_f32_e32 v53, v53
	v_cvt_pk_f16_f32 v36, v36, v37
	v_cvt_pk_f16_f32 v37, v38, v39
	v_fmamk_f32 v38, v252, 0x3a800000, v215
	v_rcp_f32_e32 v50, v50
	v_rcp_f32_e32 v51, v51
	v_rsq_f32_e32 v39, v38
	v_pk_mul_f32 v[42:43], v[42:43], v[52:53]
	v_add_u32_e32 v36, 0x80008, v36
	v_pk_mul_f32 v[44:45], v[44:45], v[50:51]
	v_cvt_pk_f16_f32 v34, v42, v43
	v_mul_f32_e32 v42, 0xbfb8aa3b, v39
	v_cvt_pk_f16_f32 v35, v44, v45
	v_pk_mul_f32 v[44:45], v[28:29], v[42:43] op_sel_hi:[1,0]
	v_pk_mul_f32 v[46:47], v[26:27], v[42:43] op_sel_hi:[1,0]
	v_pk_mul_f32 v[28:29], v[28:29], v[32:33]
	v_pk_mul_f32 v[26:27], v[26:27], v[30:31]
	v_pk_mul_f32 v[30:31], v[20:21], v[42:43] op_sel_hi:[1,0]
	v_pk_mul_f32 v[32:33], v[18:19], v[42:43] op_sel_hi:[1,0]
	v_exp_f32_e32 v30, v30
	v_exp_f32_e32 v32, v32
	v_exp_f32_e32 v31, v31
	v_exp_f32_e32 v33, v33
	v_exp_f32_e32 v46, v46
	v_exp_f32_e32 v47, v47
	v_pk_fma_f32 v[30:31], v[38:39], v[30:31], v[38:39] op_sel_hi:[0,1,0]
	v_pk_fma_f32 v[32:33], v[38:39], v[32:33], v[38:39] op_sel_hi:[0,1,0]
	v_rcp_f32_e32 v32, v32
	v_rcp_f32_e32 v30, v30
	v_rcp_f32_e32 v31, v31
	v_rcp_f32_e32 v33, v33
	v_exp_f32_e32 v44, v44
	v_exp_f32_e32 v45, v45
	v_add_u32_e32 v34, 0x80008, v34
	v_add_u32_e32 v35, 0x80008, v35
	v_add_u32_e32 v37, 0x80008, v37
	v_mad_i64_i32 v[40:41], s[4:5], v155, s47, v[122:123]
	v_and_b32_e32 v34, 0xfff0fff0, v34
	v_and_b32_e32 v35, 0xfff0fff0, v35
	v_and_b32_e32 v36, 0xfff0fff0, v36
	v_and_b32_e32 v37, 0xfff0fff0, v37
	v_lshl_add_u64 v[40:41], v[40:41], 0, v[118:119]
	v_pk_mul_f32 v[20:21], v[20:21], v[24:25]
	v_pk_mul_f32 v[18:19], v[18:19], v[22:23]
	global_store_dwordx4 v[40:41], v[34:37], off
	v_pk_mul_f32 v[22:23], v[20:21], v[30:31]
	v_pk_mul_f32 v[20:21], v[18:19], v[32:33]
	v_pk_fma_f32 v[36:37], v[38:39], v[46:47], v[38:39] op_sel_hi:[0,1,0]
	v_pk_fma_f32 v[34:35], v[38:39], v[44:45], v[38:39] op_sel_hi:[0,1,0]
	v_rcp_f32_e32 v36, v36
	v_rcp_f32_e32 v37, v37
	v_cvt_pk_f16_f32 v20, v20, v21
	v_cvt_pk_f16_f32 v21, v22, v23
	s_waitcnt vmcnt(6)
	v_fmamk_f32 v22, v121, 0x3a800000, v215
	v_rcp_f32_e32 v34, v34
	v_rcp_f32_e32 v35, v35
	v_rsq_f32_e32 v23, v22
	v_pk_mul_f32 v[26:27], v[26:27], v[36:37]
	v_add_u32_e32 v20, 0x80008, v20
	v_pk_mul_f32 v[28:29], v[28:29], v[34:35]
	v_cvt_pk_f16_f32 v18, v26, v27
	v_mul_f32_e32 v26, 0xbfb8aa3b, v23
	v_cvt_pk_f16_f32 v19, v28, v29
	v_pk_mul_f32 v[28:29], v[12:13], v[26:27] op_sel_hi:[1,0]
	v_pk_mul_f32 v[30:31], v[10:11], v[26:27] op_sel_hi:[1,0]
	v_pk_mul_f32 v[12:13], v[12:13], v[16:17]
	v_pk_mul_f32 v[10:11], v[10:11], v[14:15]
	v_pk_mul_f32 v[14:15], v[4:5], v[26:27] op_sel_hi:[1,0]
	v_pk_mul_f32 v[16:17], v[2:3], v[26:27] op_sel_hi:[1,0]
	v_exp_f32_e32 v30, v30
	v_exp_f32_e32 v28, v28
	v_exp_f32_e32 v29, v29
	v_exp_f32_e32 v31, v31
	v_exp_f32_e32 v16, v16
	v_exp_f32_e32 v14, v14
	v_exp_f32_e32 v15, v15
	v_exp_f32_e32 v17, v17
	v_add_u32_e32 v18, 0x80008, v18
	v_add_u32_e32 v19, 0x80008, v19
	v_add_u32_e32 v21, 0x80008, v21
	v_mad_i64_i32 v[24:25], s[4:5], v125, s47, v[122:123]
	v_and_b32_e32 v18, 0xfff0fff0, v18
	v_and_b32_e32 v19, 0xfff0fff0, v19
	v_and_b32_e32 v20, 0xfff0fff0, v20
	v_and_b32_e32 v21, 0xfff0fff0, v21
	v_lshl_add_u64 v[24:25], v[24:25], 0, v[118:119]
	global_store_dwordx4 v[24:25], v[18:21], off
	v_pk_fma_f32 v[14:15], v[22:23], v[14:15], v[22:23] op_sel_hi:[0,1,0]
	v_pk_fma_f32 v[16:17], v[22:23], v[16:17], v[22:23] op_sel_hi:[0,1,0]
	v_pk_fma_f32 v[18:19], v[22:23], v[28:29], v[22:23] op_sel_hi:[0,1,0]
	v_pk_fma_f32 v[20:21], v[22:23], v[30:31], v[22:23] op_sel_hi:[0,1,0]
	v_rcp_f32_e32 v20, v20
	v_rcp_f32_e32 v21, v21
	v_rcp_f32_e32 v18, v18
	v_rcp_f32_e32 v19, v19
	v_rcp_f32_e32 v16, v16
	v_rcp_f32_e32 v14, v14
	v_rcp_f32_e32 v15, v15
	v_rcp_f32_e32 v17, v17
	v_pk_mul_f32 v[4:5], v[4:5], v[8:9]
	v_pk_mul_f32 v[2:3], v[2:3], v[6:7]
	v_pk_mul_f32 v[12:13], v[12:13], v[18:19]
	v_pk_mul_f32 v[10:11], v[10:11], v[20:21]
	v_pk_mul_f32 v[6:7], v[4:5], v[14:15]
	v_pk_mul_f32 v[4:5], v[2:3], v[16:17]
	v_cvt_pk_f16_f32 v2, v10, v11
	v_cvt_pk_f16_f32 v3, v12, v13
	v_cvt_pk_f16_f32 v4, v4, v5
	v_cvt_pk_f16_f32 v5, v6, v7
	v_add_u32_e32 v2, 0x80008, v2
	v_add_u32_e32 v3, 0x80008, v3
	v_add_u32_e32 v4, 0x80008, v4
	v_add_u32_e32 v5, 0x80008, v5
	v_mad_i64_i32 v[6:7], s[4:5], v124, s47, v[122:123]
	v_and_b32_e32 v2, 0xfff0fff0, v2
	v_and_b32_e32 v3, 0xfff0fff0, v3
	v_and_b32_e32 v4, 0xfff0fff0, v4
	v_and_b32_e32 v5, 0xfff0fff0, v5
	v_lshl_add_u64 v[6:7], v[6:7], 0, v[118:119]
	global_store_dwordx4 v[6:7], v[2:5], off
	s_cbranch_vccnz .LBB0_838
	s_lshl_b32 s4, s40, 8
	s_add_i32 s4, s4, s30
	v_and_or_b32 v8, v0, 15, s4
	v_mov_b32_e32 v9, 0
	v_lshl_add_u64 v[8:9], v[8:9], 2, s[0:1]
	global_load_dword v248, v[8:9], off
	global_load_dword v249, v[8:9], off offset:64
	global_load_dword v250, v[8:9], off offset:512
	global_load_dword v251, v[8:9], off offset:576
	global_load_dword v252, v[8:9], off offset:640
	global_load_dword v253, v[8:9], off offset:128
	global_load_dword v255, v[8:9], off offset:192
	s_andn2_b64 vcc, exec, s[20:21]
	s_cbranch_vccnz .LBB0_837
	s_barrier
	s_branch .LBB0_837

; __global__ void __launch_bounds__(NWAVES * 64, 2) fwd_kernel(Args args) {
	.amdhsa_kernel _Z10fwd_kernel4Args
		.amdhsa_group_segment_fixed_size 0
		.amdhsa_private_segment_fixed_size 0
		.amdhsa_kernarg_size 424
		.amdhsa_user_sgpr_count 2
		.amdhsa_user_sgpr_dispatch_ptr 0
		.amdhsa_user_sgpr_queue_ptr 0
		.amdhsa_user_sgpr_kernarg_segment_ptr 1
		.amdhsa_user_sgpr_dispatch_id 0
		.amdhsa_user_sgpr_kernarg_preload_length 0
		.amdhsa_user_sgpr_kernarg_preload_offset 0
		.amdhsa_user_sgpr_private_segment_size 0
		.amdhsa_uses_dynamic_stack 0
		.amdhsa_enable_private_segment 0
		.amdhsa_system_sgpr_workgroup_id_x 1
		.amdhsa_system_sgpr_workgroup_id_y 0
		.amdhsa_system_sgpr_workgroup_id_z 0
		.amdhsa_system_sgpr_workgroup_info 0
		.amdhsa_system_vgpr_workitem_id 0
		.amdhsa_next_free_vgpr 256
		.amdhsa_next_free_sgpr 102
		.amdhsa_accum_offset 256
		.amdhsa_reserve_vcc 1
		.amdhsa_float_round_mode_32 0
		.amdhsa_float_round_mode_16_64 0
		.amdhsa_float_denorm_mode_32 3
		.amdhsa_float_denorm_mode_16_64 3
		.amdhsa_dx10_clamp 1
		.amdhsa_ieee_mode 1
		.amdhsa_fp16_overflow 0
		.amdhsa_tg_split 0
		.amdhsa_exception_fp_ieee_invalid_op 0
		.amdhsa_exception_fp_denorm_src 0
		.amdhsa_exception_fp_ieee_div_zero 0
		.amdhsa_exception_fp_ieee_overflow 0
		.amdhsa_exception_fp_ieee_underflow 0
		.amdhsa_exception_fp_ieee_inexact 0
		.amdhsa_exception_int_div_zero 0
	.end_amdhsa_kernel

amdhsa.kernels:
  - .agpr_count:     0
    .args:
      - .offset:         0
        .size:           168
        .value_kind:     by_value
      - .offset:         168
        .size:           4
        .value_kind:     hidden_block_count_x
      - .offset:         172
        .size:           4
        .value_kind:     hidden_block_count_y
      - .offset:         176
        .size:           4
        .value_kind:     hidden_block_count_z
      - .offset:         180
        .size:           2
        .value_kind:     hidden_group_size_x
      - .offset:         182
        .size:           2
        .value_kind:     hidden_group_size_y
      - .offset:         184
        .size:           2
        .value_kind:     hidden_group_size_z
      - .offset:         186
        .size:           2
        .value_kind:     hidden_remainder_x
      - .offset:         188
        .size:           2
        .value_kind:     hidden_remainder_y
      - .offset:         190
        .size:           2
        .value_kind:     hidden_remainder_z
      - .offset:         208
        .size:           8
        .value_kind:     hidden_global_offset_x
      - .offset:         216
        .size:           8
        .value_kind:     hidden_global_offset_y
      - .offset:         224
        .size:           8
        .value_kind:     hidden_global_offset_z
      - .offset:         232
        .size:           2
        .value_kind:     hidden_grid_dims
      - .offset:         288
        .size:           4
        .value_kind:     hidden_dynamic_lds_size
    .group_segment_fixed_size: 0
    .kernarg_segment_align: 8
    .kernarg_segment_size: 424
    .language:       OpenCL C
    .language_version:
      - 2
      - 0
    .max_flat_workgroup_size: 512
    .name:           _Z10fwd_kernel4Args
    .private_segment_fixed_size: 0
    .sgpr_count:     108
    .sgpr_spill_count: 76
    .symbol:         _Z10fwd_kernel4Args.kd
    .uniform_work_group_size: 1
    .uses_dynamic_stack: false
    .vgpr_count:     256
    .vgpr_spill_count: 0
    .wavefront_size: 64
